# P0 x-row loop: INV_FREQ load hoisted out of the loop, next row's four loads prefetched one iteration ahead into spare VGPRs (counted wait + copy at loop tail)
# baseline (speedup 1.0000x reference)
; DI void phase0(const Params& p, LAS unsigned char* lds, int tid) {
;     ...
;     float* rsx = (float*)(p.ws + OFF_RSX);
;     bf16_t* xb = (bf16_t*)(p.ws + OFF_XB);
;     f32x2* cs = (f32x2*)(p.ws + OFF_CS);
;     int cidx = blk * 512 + tid;
;     int posv = p.pos[cidx >> 5];
;     for (int row = blk * 8 + wid; row < T_; row += G * 8) {
;         const f32x4* xr = (const f32x4*)(p.x + (size_t)row * 1024) + lane;
;         f32x4 v[4]; float s = 0.f;
; #pragma unroll
;         for (int j = 0; j < 4; ++j) v[j] = __builtin_nontemporal_load(xr + 64 * j);
;         f32x2 cv; const bool docs = cidx < T_ * 32;
;         if (docs) {
;             const int i = cidx & 31;
;             const float ang = (float)posv * INV_FREQ[i];
.LBB0_95:
	v_writelane_b32 v255, s19, 12
	s_or_b64 exec, exec, s[2:3]
	s_add_u32 s18, s84, 0x3b6e0000
	s_mov_b32 s0, 0x10000
	s_addc_u32 s19, s85, 0
	v_mov_b32_e32 v254, v2
	v_add_u32_e32 v16, v23, v2
	v_cmp_gt_i32_e32 vcc, s0, v44
	s_and_saveexec_b64 s[2:3], vcc
	s_cbranch_execz .LBB0_107
	v_ashrrev_i32_e32 v2, 5, v16
	v_ashrrev_i32_e32 v3, 31, v2
	s_waitcnt lgkmcnt(0)
	v_lshl_add_u64 v[2:3], v[2:3], 2, s[38:39]
	global_load_dword v26, v[2:3], off
	v_mbcnt_lo_u32_b32 v1, -1, 0
	v_mbcnt_hi_u32_b32 v1, -1, v1
	v_and_b32_e32 v2, 64, v1
	v_add_u32_e32 v2, 64, v2
	v_xor_b32_e32 v3, 1, v1
	v_cmp_lt_i32_e32 vcc, v3, v2
	v_readlane_b32 s0, v255, 7
	v_readlane_b32 s1, v255, 8
	v_cndmask_b32_e32 v3, v1, v3, vcc
	v_lshlrev_b32_e32 v27, 2, v3
	v_xor_b32_e32 v3, 2, v1
	v_cmp_lt_i32_e32 vcc, v3, v2
	s_mov_b32 s4, s0
	s_ashr_i32 s5, s0, 31
	v_cndmask_b32_e32 v3, v1, v3, vcc
	v_lshlrev_b32_e32 v28, 2, v3
	v_xor_b32_e32 v3, 4, v1
	v_cmp_lt_i32_e32 vcc, v3, v2
	v_writelane_b32 v255, s0, 7
	s_lshl_b32 s6, s86, 3
	v_cndmask_b32_e32 v3, v1, v3, vcc
	v_lshlrev_b32_e32 v29, 2, v3
	v_xor_b32_e32 v3, 8, v1
	v_cmp_lt_i32_e32 vcc, v3, v2
	v_writelane_b32 v255, s1, 8
	s_mov_b64 s[0:1], 0x3c6e0000
	v_cndmask_b32_e32 v3, v1, v3, vcc
	v_lshlrev_b32_e32 v30, 2, v3
	v_xor_b32_e32 v3, 16, v1
	v_cmp_lt_i32_e32 vcc, v3, v2
	s_ashr_i32 s7, s6, 31
	s_mov_b32 s16, 0x6dc9c883
	v_cndmask_b32_e32 v3, v1, v3, vcc
	v_lshlrev_b32_e32 v31, 2, v3
	v_xor_b32_e32 v3, 32, v1
	v_cmp_lt_i32_e32 vcc, v3, v2
	s_lshl_b32 s22, s86, 9
	s_lshl_b64 s[8:9], s[6:7], 2
	v_cndmask_b32_e32 v1, v1, v3, vcc
	v_lshlrev_b32_e32 v32, 2, v1
	v_ashrrev_i32_e32 v1, 31, v0
	v_lshl_add_u64 v[0:1], v[0:1], 0, s[4:5]
	v_lshl_add_u64 v[2:3], v[0:1], 2, s[84:85]
	v_lshl_add_u64 v[18:19], v[2:3], 0, s[0:1]
	v_lshlrev_b64 v[2:3], 11, v[0:1]
	v_lshl_or_b32 v2, v7, 3, v2
	v_lshlrev_b64 v[0:1], 12, v[0:1]
	v_lshl_add_u64 v[2:3], s[84:85], 0, v[2:3]
	s_mov_b64 s[0:1], 0x22000400
	v_lshl_or_b32 v0, v7, 4, v0
	v_lshl_add_u64 v[20:21], v[2:3], 0, s[0:1]
	v_lshl_add_u64 v[0:1], s[36:37], 0, v[0:1]
	s_mov_b64 s[0:1], 0xc00
	v_cmp_eq_u32_e32 vcc, 0, v7
	s_lshl_b64 s[10:11], s[6:7], 11
	v_lshl_add_u64 v[22:23], v[0:1], 0, s[0:1]
	s_lshl_b64 s[14:15], s[6:7], 12
	s_mov_b64 s[12:13], 0
	s_mov_b32 s7, 0x200000
	s_mov_b32 s17, 0x3fc45f30
	v_mov_b32_e32 v33, 0x358637bd
	s_mov_b32 s23, 0x800000
	s_mov_b32 s24, 0xffff
	v_and_b32_e32 v17, 31, v16
	v_lshlrev_b32_e32 v17, 2, v17
	s_getpc_b64 s[20:21]
	s_add_u32 s20, s20, _ZL8INV_FREQ@rel32@lo+4
	s_addc_u32 s21, s21, _ZL8INV_FREQ@rel32@hi+12
	global_load_dword v217, v17, s[20:21]
	global_load_dwordx4 v[12:15], v[22:23], off offset:-3072 nt
	global_load_dwordx4 v[8:11], v[22:23], off offset:-2048 nt
	global_load_dwordx4 v[4:7], v[22:23], off offset:-1024 nt
	global_load_dwordx4 v[0:3], v[22:23], off nt
	s_waitcnt vmcnt(0)
	s_branch .LBB0_99

; DI unsigned pk2(float lo, float hi) { f32x2 v = {lo, hi}; bf2_t r = __builtin_convertvector(v, bf2_t); return __builtin_bit_cast(unsigned, r); }
; DI float sq4(f32x4 v) { return (v.x * v.x + v.y * v.y) + (v.z * v.z + v.w * v.w); }
; DI void phase0(const Params& p, LAS unsigned char* lds, int tid) {
;     ...
;     for (int row = blk * 8 + wid; row < T_; row += G * 8) {
;         const f32x4* xr = (const f32x4*)(p.x + (size_t)row * 1024) + lane;
;         f32x4 v[4]; float s = 0.f;
; #pragma unroll
;         for (int j = 0; j < 4; ++j) v[j] = __builtin_nontemporal_load(xr + 64 * j);
;         f32x2 cv; const bool docs = cidx < T_ * 32;
;         if (docs) {
;             const int i = cidx & 31;
;             const float ang = (float)posv * INV_FREQ[i];
;             const double rev = (double)ang * 0.15915494309189535;
;             const float fr = (float)(rev - __builtin_rint(rev));
;             cv.x = __builtin_amdgcn_cosf(fr); cv.y = __builtin_amdgcn_sinf(fr);
;         }
; #pragma unroll
;         for (int j = 0; j < 4; ++j) s += sq4(v[j]);
;         s = wave_sum(s);
;         if (lane == 0) rsx[row] = rsqrtf(s * (1.f / 1024.f) + EPS_);
;         u32x2* o = (u32x2*)(xb + (size_t)row * 1024) + lane;
; #pragma unroll
;         for (int j = 0; j < 4; ++j) { u32x2 w; w.x = pk2(v[j].x, v[j].y); w.y = pk2(v[j].z, v[j].w); o[64 * j] = w; }
;         if (docs) { cs[cidx] = cv; cidx += G * 512; if (cidx < T_ * 32) posv = p.pos[cidx >> 5]; }
.LBB0_98:
	s_or_b64 exec, exec, s[4:5]
	s_waitcnt vmcnt(5)
	v_mov_b32_e32 v0, v200
	v_mov_b32_e32 v1, v201
	v_mov_b32_e32 v2, v202
	v_mov_b32_e32 v3, v203
	v_mov_b32_e32 v4, v204
	v_mov_b32_e32 v5, v205
	v_mov_b32_e32 v6, v206
	v_mov_b32_e32 v7, v207
	v_mov_b32_e32 v8, v208
	v_mov_b32_e32 v9, v209
	v_mov_b32_e32 v10, v210
	v_mov_b32_e32 v11, v211
	v_mov_b32_e32 v12, v212
	v_mov_b32_e32 v13, v213
	v_mov_b32_e32 v14, v214
	v_mov_b32_e32 v15, v215
	v_add_u32_e32 v44, s6, v44
	v_cmp_lt_i32_e64 s[0:1], s24, v44
	v_lshl_add_u64 v[18:19], v[18:19], 0, s[8:9]
	v_lshl_add_u64 v[20:21], v[20:21], 0, s[10:11]
	s_or_b64 s[12:13], s[0:1], s[12:13]
	v_lshl_add_u64 v[22:23], v[22:23], 0, s[14:15]
	s_andn2_b64 exec, exec, s[12:13]
	s_cbranch_execz .LBB0_106
.LBB0_99:
	v_readfirstlane_b32 s98, v44
	s_add_i32 s98, s98, s6
	s_cmp_le_i32 s98, s24
	s_cbranch_scc1 .Lp0_pf
	s_waitcnt vmcnt(0)
	s_branch .Lp0_join
.Lp0_pf:
	v_lshl_add_u64 v[218:219], v[22:23], 0, s[14:15]
	global_load_dwordx4 v[212:215], v[218:219], off offset:-3072 nt
	global_load_dwordx4 v[208:211], v[218:219], off offset:-2048 nt
	global_load_dwordx4 v[204:207], v[218:219], off offset:-1024 nt
	global_load_dwordx4 v[200:203], v[218:219], off nt
.Lp0_join:
	v_cmp_gt_i32_e64 s[0:1], s7, v16
	s_and_saveexec_b64 s[4:5], s[0:1]
	s_cbranch_execz .LBB0_101
	s_waitcnt vmcnt(4)
	v_cvt_f32_i32_e32 v24, v26
	v_mul_f32_e32 v17, v217, v24
	v_cvt_f64_f32_e32 v[24:25], v17
	s_waitcnt lgkmcnt(0)
	v_mul_f64 v[34:35], v[24:25], s[16:17]
	v_rndne_f64_e32 v[34:35], v[34:35]
	v_fma_f64 v[24:25], v[24:25], s[16:17], -v[34:35]
	v_cvt_f32_f64_e32 v17, v[24:25]
	v_cos_f32_e32 v24, v17
	v_sin_f32_e32 v25, v17
.LBB0_101:
	s_or_b64 exec, exec, s[4:5]
	v_mul_f32_e32 v17, v13, v13
	s_waitcnt lgkmcnt(0)
	v_mul_f32_e32 v34, v15, v15
	v_fmac_f32_e32 v17, v12, v12
	v_fmac_f32_e32 v34, v14, v14
	v_add_f32_e32 v17, v17, v34
	v_mul_f32_e32 v34, v9, v9
	v_mul_f32_e32 v35, v11, v11
	v_fmac_f32_e32 v34, v8, v8
	v_fmac_f32_e32 v35, v10, v10
	v_add_f32_e32 v34, v34, v35
	v_add_f32_e32 v17, v17, v34
	v_mul_f32_e32 v34, v5, v5
	v_mul_f32_e32 v35, v7, v7
	v_fmac_f32_e32 v34, v4, v4
	v_fmac_f32_e32 v35, v6, v6
	v_add_f32_e32 v34, v34, v35
	v_add_f32_e32 v17, v17, v34
	v_mul_f32_e32 v34, v1, v1
	v_mul_f32_e32 v35, v3, v3
	v_fmac_f32_e32 v34, v0, v0
	v_fmac_f32_e32 v35, v2, v2
	v_add_f32_e32 v34, v34, v35
	v_add_f32_e32 v17, v17, v34
	ds_bpermute_b32 v34, v27, v17
	s_waitcnt lgkmcnt(0)
	v_add_f32_e32 v17, v17, v34
	ds_bpermute_b32 v34, v28, v17
	s_waitcnt lgkmcnt(0)
	v_add_f32_e32 v17, v17, v34
	ds_bpermute_b32 v34, v29, v17
	s_waitcnt lgkmcnt(0)
	v_add_f32_e32 v17, v17, v34
	ds_bpermute_b32 v34, v30, v17
	s_waitcnt lgkmcnt(0)
	v_add_f32_e32 v17, v17, v34
	ds_bpermute_b32 v34, v31, v17
	s_waitcnt lgkmcnt(0)
	v_add_f32_e32 v17, v17, v34
	ds_bpermute_b32 v34, v32, v17
	s_and_saveexec_b64 s[20:21], vcc
	s_cbranch_execz .LBB0_103
	s_waitcnt lgkmcnt(0)
	v_add_f32_e32 v17, v17, v34
	v_fmamk_f32 v17, v17, 0x3a800000, v33
	v_mul_f32_e32 v34, 0x4b800000, v17
	v_cmp_gt_f32_e64 s[4:5], s23, v17
	s_nop 1
	v_cndmask_b32_e64 v17, v17, v34, s[4:5]
	v_rsq_f32_e32 v17, v17
	s_nop 0
	v_mul_f32_e32 v34, 0x45800000, v17
	v_cndmask_b32_e64 v17, v17, v34, s[4:5]
	global_store_dword v[18:19], v17, off
